# prompt attention unit prologue: compiler's over-drain vmcnt(3/2/1/0) ladder (Q loads already drained by the explicit vmcnt(0)) reduced to its lgkmcnt parts, so tile 2's LDS-DMA stays in flight under Q
# speedup vs baseline: 1.0070x; 1.0070x over previous
; #define GAS __attribute__((address_space(1)))
; __device__ __forceinline__ int v_rd_base(int lane) { return ((lane & 3) << 3) | (((lane >> 2) & 3) << 6) | (((lane >> 4) & 1) << 5) | (((lane >> 5) & 1) << 8); }
; #define EXPALL(X0, X1) do { _Pragma("unroll") for (int r = 0; r < 16; ++r) { EX2(X0, r); EX2(X1, r); } } while (0)
; __device__ __forceinline__ void attn_prompt(Frame& F, int b, int h, int qb, float lam, float mshift) {
;     ...
;     { const bf16* Qw = QB + (qrow0 + 32 * rb + r32) * DM + h * 128 + m * 64 + hi * 8;
; #pragma unroll
;       for (int d0 = 0; d0 < 4; ++d0) qr[d0] = *(const GAS bf16x8*)(Qw + d0 * 16); }
;     const int vbase = (int)lds0 + 16384 + v_rd_base(lane);
;     f32x16 o[4]; f32x16 ol;
;     const bf16x8 ones = {0x3F80, 0x3F80, 0x3F80, 0x3F80, 0x3F80, 0x3F80, 0x3F80, 0x3F80};
; #pragma unroll
;     for (int d = 0; d < 4; ++d)
; #pragma unroll
;         for (int r = 0; r < 16; ++r) o[d][r] = 0.f;
; #pragma unroll
;     for (int r = 0; r < 16; ++r) ol[r] = 0.f;
;     f32x16 pA0, pA1, pB0, pB1; bf16x8 pa0, pa1, pa2, pa3; f32x16 CF;
;     ...
;     asm volatile("s_waitcnt vmcnt(0)" ::: "memory"); __syncthreads();
;     { const float cf = TB[63];
; #pragma unroll
;       for (int r = 0; r < 16; ++r) CF[r] = cf; }
;     { const int j2 = (2 < NT) ? 2 : NT - 1; DMA_TILE(j2, 2 * P_SLOT); }
;     QKT(pA0, pA1, 0, 0); EXPALL(pA0, pA1);
.LBB0_499:
	s_or_b64 exec, exec, s[54:55]
	s_lshl_b32 s34, s58, 1
	s_lshl_b32 s14, s58, 7
	s_or_b32 s3, s76, s14
	s_or_b32 s2, s34, 1
	s_lshl_b64 s[52:53], s[52:53], 11
	v_and_b32_e32 v217, 31, v219
	s_add_u32 s52, s52, s14
	s_addc_u32 s53, s53, 0
	v_or_b32_e32 v2, s76, v217
	v_or_b32_e32 v2, s52, v2
	v_mov_b32_e32 v3, s53
	v_lshlrev_b64 v[2:3], 11, v[2:3]
	v_and_b32_e32 v218, 63, v219
	v_lshl_add_u64 v[2:3], s[24:25], 0, v[2:3]
	s_lshl_b32 s54, s10, 1
	s_mov_b32 s55, s11
	v_lshrrev_b32_e32 v216, 5, v218
	v_lshl_add_u64 v[2:3], v[2:3], 0, s[54:55]
	s_lshl_b32 s10, s69, 1
	v_lshl_add_u64 v[2:3], v[2:3], 0, s[10:11]
	s_waitcnt vmcnt(16)
	v_lshlrev_b32_e32 v194, 4, v216
	v_mov_b32_e32 v195, v211
	v_lshl_add_u64 v[2:3], v[2:3], 0, v[194:195]
	global_load_dwordx4 v[174:177], v[2:3], off
	global_load_dwordx4 v[170:173], v[2:3], off offset:32
	global_load_dwordx4 v[166:169], v[2:3], off offset:64
	global_load_dwordx4 v[162:165], v[2:3], off offset:96
	s_cmp_gt_i32 s58, 0
	s_cselect_b64 s[58:59], -1, 0
	s_and_b64 s[60:61], s[58:59], exec
	s_cselect_b32 s60, 2, s2
	s_mov_b32 s61, s11
	s_lshl_b64 s[60:61], s[60:61], 17
	s_add_u32 s64, s0, s60
	v_mov_b32_e32 v2, s95
	s_addc_u32 s65, s1, s61
	s_waitcnt vmcnt(0)
	s_waitcnt lgkmcnt(0)
	s_barrier
	ds_read_b32 v82, v2
	s_add_u32 s60, s56, s60
	v_lshl_add_u64 v[2:3], s[64:65], 0, v[210:211]
	s_addc_u32 s61, s57, s61
	s_add_i32 s55, s92, 0x10000
	s_mov_b32 s66, m0
	s_mov_b32 m0, s55
	s_nop 0
	global_load_lds_dwordx4 v[2:3], off
	s_mov_b32 m0, s66
	v_lshl_add_u64 v[2:3], s[64:65], 0, v[198:199]
	s_add_i32 s55, s92, 0x10400
	s_mov_b32 s64, m0
	s_mov_b32 m0, s55
	s_nop 0
	global_load_lds_dwordx4 v[2:3], off
	s_mov_b32 m0, s64
	v_lshl_add_u64 v[2:3], v[196:197], 1, s[60:61]
	s_add_i32 s55, s93, 0x10000
	s_mov_b32 s60, m0
	s_mov_b32 m0, s55
	s_nop 0
	global_load_lds_dwordx4 v[2:3], off
	s_mov_b32 m0, s60
	v_lshl_add_u64 v[2:3], v[2:3], 0, s[50:51]
	s_add_i32 s55, s93, 0x10400
	s_mov_b32 s60, m0
	s_mov_b32 m0, s55
	s_nop 0
	global_load_lds_dwordx4 v[2:3], off
	s_mov_b32 m0, s60
	v_lshlrev_b32_e32 v2, 4, v219
	v_or_b32_e32 v42, s10, v194
	v_lshlrev_b32_e32 v195, 8, v217
	v_and_b32_e32 v43, 0x70, v2
	v_xad_u32 v200, v42, v43, v195
	v_add_u32_e32 v2, 0, v200
	ds_read_b128 v[38:41], v2
	ds_read_b128 v[34:37], v2 offset:8192
	s_waitcnt lgkmcnt(2)
	v_mov_b32_e32 v83, v82
	v_mov_b32_e32 v84, v82
	v_mov_b32_e32 v85, v82
	v_mov_b32_e32 v86, v82
	v_mov_b32_e32 v87, v82
	v_mov_b32_e32 v88, v82
	v_mov_b32_e32 v89, v82
	v_mov_b32_e32 v90, v82
	v_mov_b32_e32 v91, v82
	v_mov_b32_e32 v92, v82
	v_mov_b32_e32 v93, v82
	v_mov_b32_e32 v94, v82
	v_mov_b32_e32 v95, v82
	v_mov_b32_e32 v96, v82
	v_mov_b32_e32 v97, v82
	s_cmpk_gt_u32 s3, 0xbf
	s_mov_b64 s[60:61], -1
	s_cbranch_scc0 .LBB0_501
	s_waitcnt lgkmcnt(1)
	v_mfma_f32_32x32x16_bf16 v[2:17], v[38:41], v[174:177], v[82:97]
	s_mov_b64 s[60:61], 0
	s_waitcnt lgkmcnt(0)
	v_mfma_f32_32x32x16_bf16 v[18:33], v[34:37], v[174:177], v[82:97]
.LBB0_501:
	s_andn2_b64 vcc, exec, s[60:61]
	v_or_b32_e32 v201, s3, v217
	s_cbranch_vccnz .LBB0_503
	s_nop 5
	v_lshlrev_b32_e32 v2, 2, v216
	v_sub_u32_e32 v2, v2, v201
	s_add_i32 s10, 0, 0x20400
	v_lshl_add_u32 v32, v2, 2, s10
	ds_read2_b32 v[2:3], v32 offset0:191 offset1:192
	ds_read2_b32 v[4:5], v32 offset0:193 offset1:194
	ds_read2_b32 v[6:7], v32 offset0:199 offset1:200
	ds_read2_b32 v[8:9], v32 offset0:201 offset1:202
	ds_read2_b32 v[10:11], v32 offset0:207 offset1:208
	ds_read2_b32 v[12:13], v32 offset0:209 offset1:210
	ds_read2_b32 v[14:15], v32 offset0:215 offset1:216
	ds_read2_b32 v[16:17], v32 offset0:217 offset1:218
	ds_read2_b32 v[18:19], v32 offset0:223 offset1:224
	ds_read2_b32 v[20:21], v32 offset0:225 offset1:226
	ds_read2_b32 v[22:23], v32 offset0:231 offset1:232
	ds_read2_b32 v[24:25], v32 offset0:233 offset1:234
	ds_read2_b32 v[26:27], v32 offset0:239 offset1:240
	ds_read2_b32 v[28:29], v32 offset0:241 offset1:242
	ds_read2_b32 v[30:31], v32 offset0:247 offset1:248
	ds_read2_b32 v[32:33], v32 offset0:249 offset1:250
	s_waitcnt lgkmcnt(8)
	v_mfma_f32_32x32x16_bf16 v[2:17], v[38:41], v[174:177], v[2:17]
	s_waitcnt lgkmcnt(0)
	v_mfma_f32_32x32x16_bf16 v[18:33], v[34:37], v[174:177], v[18:33]
; #define EXPALL(X0, X1) do { _Pragma("unroll") for (int r = 0; r < 16; ++r) { EX2(X0, r); EX2(X1, r); } } while (0)
; #define ROT() do { s_prev = s_cur; s_cur = s_next; s_next = s_nn; s_nn = (s_nn == 3 * P_SLOT) ? 0 : s_nn + P_SLOT; } while (0)
; __device__ __forceinline__ void attn_prompt(Frame& F, int b, int h, int qb, float lam, float mshift) {
;     ...
; #pragma unroll
;     for (int d = 0; d < 4; ++d)
; #pragma unroll
;         for (int r = 0; r < 16; ++r) o[d][r] = 0.f;
; #pragma unroll
;     for (int r = 0; r < 16; ++r) ol[r] = 0.f;
;     f32x16 pA0, pA1, pB0, pB1; bf16x8 pa0, pa1, pa2, pa3; f32x16 CF;
;     ...
;     int s_prev = 0, s_cur = 0, s_next = P_SLOT, s_nn = 2 * P_SLOT;
;     ...
;     asm volatile("s_waitcnt vmcnt(0)" ::: "memory"); __syncthreads();
;     { const float cf = TB[63];
; #pragma unroll
;       for (int r = 0; r < 16; ++r) CF[r] = cf; }
;     { const int j2 = (2 < NT) ? 2 : NT - 1; DMA_TILE(j2, 2 * P_SLOT); }
;     QKT(pA0, pA1, 0, 0); EXPALL(pA0, pA1);
;     ROT();
.LBB0_503:
	v_add_u32_e32 v44, 0, v195
	v_bitop3_b32 v202, v42, v43, 32 bitop3:0x36
	s_waitcnt lgkmcnt(1)
	v_add_u32_e32 v38, v44, v202
	s_waitcnt lgkmcnt(0)
	ds_read_b128 v[34:37], v38
	ds_read_b128 v[38:41], v38 offset:8192
	v_bitop3_b32 v203, v42, v43, 64 bitop3:0x36
	v_add_u32_e32 v45, v44, v203
	s_waitcnt lgkmcnt(1)
	v_mfma_f32_32x32x16_bf16 v[2:17], v[34:37], v[170:173], v[2:17]
	v_bitop3_b32 v204, v42, v43, s84 bitop3:0x36
	v_add_u32_e32 v42, v44, v204
	v_lshlrev_b32_e32 v43, 3, v218
	s_lshr_b32 s83, s3, 6
	s_add_i32 s3, 0, 0x4000
	s_andn2_b64 vcc, exec, s[58:59]
	s_waitcnt lgkmcnt(0)
	v_mfma_f32_32x32x16_bf16 v[18:33], v[38:41], v[170:173], v[18:33]
	ds_read_b128 v[34:37], v45
	ds_read_b128 v[38:41], v45 offset:8192
	s_waitcnt lgkmcnt(0)
	v_mfma_f32_32x32x16_bf16 v[18:33], v[38:41], v[166:169], v[18:33]
	v_lshlrev_b32_e32 v38, 4, v218
	v_and_b32_e32 v44, 0xc0, v38
	ds_read_b128 v[38:41], v42 offset:8192
	v_mfma_f32_32x32x16_bf16 v[2:17], v[34:37], v[166:169], v[2:17]
	ds_read_b128 v[34:37], v42
	s_waitcnt lgkmcnt(0)
	v_mfma_f32_32x32x16_bf16 v[2:17], v[34:37], v[162:165], v[2:17]
	v_lshlrev_b32_e32 v35, 1, v218
	v_and_or_b32 v34, v43, 24, v44
	v_and_b32_e32 v35, 32, v35
	v_and_b32_e32 v36, 0x100, v43
	v_or3_b32 v34, v34, v35, v36
	v_add_u32_e32 v220, s3, v34
	s_nop 5
	v_exp_f32_e32 v146, v2
	v_mfma_f32_32x32x16_bf16 v[18:33], v[38:41], v[162:165], v[18:33]
	v_exp_f32_e32 v147, v3
	v_exp_f32_e32 v148, v4
	v_exp_f32_e32 v149, v5
	v_exp_f32_e32 v150, v6
	v_exp_f32_e32 v151, v7
	v_exp_f32_e32 v152, v8
	v_exp_f32_e32 v153, v9
	s_nop 4
	v_exp_f32_e32 v159, v18
	v_exp_f32_e32 v160, v19
	v_exp_f32_e32 v161, v20
	v_exp_f32_e32 v199, v21
	v_exp_f32_e32 v224, v22
	v_exp_f32_e32 v225, v23
	v_exp_f32_e32 v226, v24
	v_exp_f32_e32 v227, v25
	v_exp_f32_e32 v154, v10
	v_exp_f32_e32 v138, v26
	v_exp_f32_e32 v155, v11
	v_exp_f32_e32 v139, v27
	v_exp_f32_e32 v156, v12
	v_exp_f32_e32 v140, v28
	v_exp_f32_e32 v157, v13
	v_exp_f32_e32 v141, v29
	v_exp_f32_e32 v158, v14
	v_exp_f32_e32 v142, v30
	v_exp_f32_e32 v221, v15
	v_exp_f32_e32 v143, v31
	v_exp_f32_e32 v222, v16
	v_exp_f32_e32 v144, v32
	v_exp_f32_e32 v223, v17
	v_exp_f32_e32 v145, v33
	s_cbranch_vccnz .LBB0_516
	s_add_i32 s10, s76, s14
	v_add_lshl_u32 v2, s10, v217, 2
	v_sub_u32_e32 v2, v194, v2
	v_readlane_b32 s10, v255, 19
	v_mov_b32_e32 v18, 0
	s_add_i32 s84, s83, -2
	s_mov_b32 s66, -1
	s_add_i32 s3, s34, -1
	v_add_u32_e32 v205, s10, v2
	s_mov_b32 s65, 0x18000
	s_mov_b32 s70, 0x10000
	s_mov_b32 s55, 0x8000
	s_mov_b32 s14, 0
	v_mov_b32_e32 v19, v18
	v_mov_b32_e32 v20, v18
	v_mov_b32_e32 v21, v18
	v_mov_b32_e32 v22, v18
	v_mov_b32_e32 v23, v18
	v_mov_b32_e32 v24, v18
	v_mov_b32_e32 v25, v18
	v_mov_b32_e32 v26, v18
	v_mov_b32_e32 v27, v18
	v_mov_b32_e32 v28, v18
	v_mov_b32_e32 v29, v18
	v_mov_b32_e32 v30, v18
	v_mov_b32_e32 v31, v18
	v_mov_b32_e32 v32, v18
	v_mov_b32_e32 v33, v18
	v_mov_b32_e32 v66, v18
	v_mov_b32_e32 v67, v18
	v_mov_b32_e32 v68, v18
	v_mov_b32_e32 v69, v18
	v_mov_b32_e32 v70, v18
	v_mov_b32_e32 v71, v18
	v_mov_b32_e32 v72, v18
	v_mov_b32_e32 v73, v18
	v_mov_b32_e32 v74, v18
	v_mov_b32_e32 v75, v18
	v_mov_b32_e32 v76, v18
	v_mov_b32_e32 v77, v18
	v_mov_b32_e32 v78, v18
	v_mov_b32_e32 v79, v18
	v_mov_b32_e32 v80, v18
	v_mov_b32_e32 v81, v18
	v_mov_b32_e32 v50, v18
	v_mov_b32_e32 v51, v18
	v_mov_b32_e32 v52, v18
	v_mov_b32_e32 v53, v18
	v_mov_b32_e32 v54, v18
	v_mov_b32_e32 v55, v18
	v_mov_b32_e32 v56, v18
	v_mov_b32_e32 v57, v18
	v_mov_b32_e32 v58, v18
	v_mov_b32_e32 v59, v18
	v_mov_b32_e32 v60, v18
	v_mov_b32_e32 v61, v18
	v_mov_b32_e32 v62, v18
	v_mov_b32_e32 v63, v18
	v_mov_b32_e32 v64, v18
	v_mov_b32_e32 v65, v18
	v_mov_b32_e32 v34, v18
	v_mov_b32_e32 v35, v18
	v_mov_b32_e32 v36, v18
	v_mov_b32_e32 v37, v18
	v_mov_b32_e32 v38, v18
	v_mov_b32_e32 v39, v18
	v_mov_b32_e32 v40, v18
	v_mov_b32_e32 v41, v18
	v_mov_b32_e32 v42, v18
	v_mov_b32_e32 v43, v18
	v_mov_b32_e32 v44, v18
	v_mov_b32_e32 v45, v18
	v_mov_b32_e32 v46, v18
	v_mov_b32_e32 v47, v18
	v_mov_b32_e32 v48, v18
	v_mov_b32_e32 v49, v18
	v_mov_b32_e32 v2, v18
	v_mov_b32_e32 v3, v18
	v_mov_b32_e32 v4, v18
	v_mov_b32_e32 v5, v18
	v_mov_b32_e32 v6, v18
	v_mov_b32_e32 v7, v18
	v_mov_b32_e32 v8, v18
	v_mov_b32_e32 v9, v18
	v_mov_b32_e32 v10, v18
	v_mov_b32_e32 v11, v18
	v_mov_b32_e32 v12, v18
	v_mov_b32_e32 v13, v18
	v_mov_b32_e32 v14, v18
	v_mov_b32_e32 v15, v18
	v_mov_b32_e32 v16, v18
	v_mov_b32_e32 v17, v18
